# grid-barrier census (first barrier): the 16 per-XCC counter loads issued together instead of ~11 serialized sc1 round trips
# speedup vs baseline: 1.0064x; 1.0009x over previous
.LBB0_1013:
	v_readlane_b32 s6, v254, 8
	global_load_dword v4, v1, s[18:19] sc1
	global_load_dword v0, v1, s[20:21] sc1
	s_waitcnt lgkmcnt(0)
	global_load_dword v2, v1, s[22:23] sc1
	global_load_dword v3, v1, s[24:25] sc1
	v_readlane_b32 s4, v253, 8
	v_readlane_b32 s5, v253, 9
	s_nop 4
	global_load_dword v5, v1, s[4:5] sc1
	v_readlane_b32 s4, v253, 10
	v_readlane_b32 s5, v253, 11
	s_nop 4
	global_load_dword v6, v1, s[4:5] sc1
	v_readlane_b32 s4, v253, 12
	v_readlane_b32 s5, v253, 13
	s_nop 4
	global_load_dword v7, v1, s[4:5] sc1
	v_readlane_b32 s4, v253, 14
	v_readlane_b32 s5, v253, 15
	s_nop 4
	global_load_dword v8, v1, s[4:5] sc1
	v_readlane_b32 s4, v253, 16
	v_readlane_b32 s5, v253, 17
	s_nop 4
	global_load_dword v9, v1, s[4:5] sc1
	v_readlane_b32 s4, v253, 18
	v_readlane_b32 s5, v253, 19
	s_nop 4
	global_load_dword v10, v1, s[4:5] sc1
	v_readlane_b32 s4, v253, 20
	v_readlane_b32 s5, v253, 21
	s_nop 4
	global_load_dword v11, v1, s[4:5] sc1
	v_readlane_b32 s4, v253, 22
	v_readlane_b32 s5, v253, 23
	s_nop 4
	global_load_dword v12, v1, s[4:5] sc1
	v_readlane_b32 s4, v253, 24
	v_readlane_b32 s5, v253, 25
	s_nop 4
	global_load_dword v13, v1, s[4:5] sc1
	v_readlane_b32 s4, v253, 26
	v_readlane_b32 s5, v253, 27
	s_nop 4
	global_load_dword v14, v1, s[4:5] sc1
	v_readlane_b32 s4, v253, 28
	v_readlane_b32 s5, v253, 29
	s_nop 4
	global_load_dword v15, v1, s[4:5] sc1
	v_readlane_b32 s4, v253, 30
	v_readlane_b32 s5, v253, 31
	s_nop 4
	global_load_dword v16, v1, s[4:5] sc1
	s_mov_b64 s[4:5], -1
	s_waitcnt vmcnt(0)
	v_add_u32_e32 v17, v0, v4
	v_add_u32_e32 v17, v17, v2
	v_add_u32_e32 v17, v17, v3
	v_add_u32_e32 v17, v17, v5
	v_add_u32_e32 v17, v17, v6
	v_add_u32_e32 v17, v17, v7
	v_add_u32_e32 v17, v17, v8
	v_add_u32_e32 v17, v17, v9
	v_add_u32_e32 v17, v17, v10
	v_add_u32_e32 v17, v17, v11
	v_add_u32_e32 v17, v17, v12
	v_add_u32_e32 v17, v17, v13
	v_add_u32_e32 v17, v17, v14
	v_add_u32_e32 v17, v17, v15
	v_add_u32_e32 v17, v17, v16
	v_cmp_eq_u32_e32 vcc, s6, v17
	s_mov_b64 s[6:7], -1
	s_cbranch_vccnz .LBB0_1012
	s_and_b32 s4, s2, 0xff
	s_cmp_eq_u32 s4, 0
	s_mov_b64 s[4:5], -1
	s_mov_b64 s[8:9], -1
	s_sleep 1
	s_cbranch_scc1 .LBB0_1017
	s_and_b64 vcc, exec, s[8:9]
	s_cbranch_vccz .LBB0_1012
